# v37: v34 + [u|z] epilogue: the silu scale and +1 steps issued as packed f32 ops (same arithmetic, 8 fewer vector instructions per row)
# speedup vs baseline: 1.0015x; 1.0015x over previous
.LBB0_469:
	s_mov_b32 s0, 0xbb7be14b
	s_mov_b32 s2, 0x3bcff2a2
	s_mov_b32 s28, 0xbc40d0ac
	s_mov_b32 s30, 0x3cb76c34
	s_mov_b32 s48, 0xbd17b858
	s_mov_b32 s50, 0x3d6537d1
	s_mov_b32 s52, 0xbdacab04
	s_mov_b32 s54, 0x3e342bfa
	v_mov_b32_e32 v198, s0
	v_mov_b32_e32 v190, 0xbfb8aa3b
	v_lshl_or_b32 v146, s47, 7, v176
	v_lshlrev_b32_e32 v145, 12, v142
	v_lshl_add_u32 v182, v146, 1, v145
	v_add_u32_e32 v183, 0x10000, v182
	v_add_u32_e32 v184, 0x20000, v182
	v_add_u32_e32 v185, 0x30000, v182
	v_add_u32_e32 v186, 0x80000, v182
	v_add_u32_e32 v187, 0x90000, v182
	v_add_u32_e32 v188, 0xa0000, v182
	v_add_u32_e32 v189, 0xb0000, v182
	s_waitcnt vmcnt(0)
	v_pk_mul_f32 v[128:129], v[128:129], v[236:237] op_sel_hi:[1,0]
	v_pk_mul_f32 v[130:131], v[130:131], v[236:237] op_sel_hi:[1,0]
	v_pk_mul_f32 v[120:121], v[120:121], v[236:237] op_sel_hi:[1,0]
	v_pk_mul_f32 v[122:123], v[122:123], v[236:237] op_sel_hi:[1,0]
	v_pk_mul_f32 v[124:125], v[124:125], v[236:237] op_sel_hi:[1,0]
	v_pk_mul_f32 v[126:127], v[126:127], v[236:237] op_sel_hi:[1,0]
	v_pk_mul_f32 v[116:117], v[116:117], v[236:237] op_sel_hi:[1,0]
	v_pk_mul_f32 v[118:119], v[118:119], v[236:237] op_sel_hi:[1,0]
	v_med3_f32 v158, v128, -4.0, 4.0
	v_med3_f32 v164, v130, -4.0, 4.0
	v_pk_mul_f32 v[170:171], v[124:125], v[190:191] op_sel_hi:[1,0]
	v_med3_f32 v159, v129, -4.0, 4.0
	v_med3_f32 v165, v131, -4.0, 4.0
	v_pk_mul_f32 v[172:173], v[126:127], v[190:191] op_sel_hi:[1,0]
	v_pk_mul_f32 v[160:161], v[158:159], v[158:159]
	v_pk_mul_f32 v[166:167], v[164:165], v[164:165]
	v_exp_f32_e32 v170, v170
	v_pk_fma_f32 v[160:161], v[160:161], s[72:73], -1.0 op_sel_hi:[1,0,0]
	v_pk_fma_f32 v[166:167], v[166:167], s[72:73], -1.0 op_sel_hi:[1,0,0]
	v_exp_f32_e32 v171, v171
	v_pk_fma_f32 v[162:163], v[160:161], s[74:75], v[198:199] op_sel_hi:[1,0,0]
	v_pk_fma_f32 v[168:169], v[166:167], s[74:75], v[198:199] op_sel_hi:[1,0,0]
	v_exp_f32_e32 v172, v172
	v_pk_fma_f32 v[162:163], v[160:161], v[162:163], s[2:3] op_sel_hi:[1,1,0]
	v_pk_fma_f32 v[168:169], v[166:167], v[168:169], s[2:3] op_sel_hi:[1,1,0]
	v_exp_f32_e32 v173, v173
	v_pk_fma_f32 v[162:163], v[160:161], v[162:163], s[28:29] op_sel_hi:[1,1,0]
	v_pk_fma_f32 v[168:169], v[166:167], v[168:169], s[28:29] op_sel_hi:[1,1,0]
	v_pk_add_f32 v[170:171], v[170:171], 1.0 op_sel_hi:[1,0]
	v_pk_fma_f32 v[162:163], v[160:161], v[162:163], s[30:31] op_sel_hi:[1,1,0]
	v_pk_fma_f32 v[168:169], v[166:167], v[168:169], s[30:31] op_sel_hi:[1,1,0]
	v_pk_add_f32 v[172:173], v[172:173], 1.0 op_sel_hi:[1,0]
	v_pk_fma_f32 v[162:163], v[160:161], v[162:163], s[48:49] op_sel_hi:[1,1,0]
	v_pk_fma_f32 v[168:169], v[166:167], v[168:169], s[48:49] op_sel_hi:[1,1,0]
	v_rcp_f32_e32 v178, v170
	v_pk_fma_f32 v[162:163], v[160:161], v[162:163], s[50:51] op_sel_hi:[1,1,0]
	v_pk_fma_f32 v[168:169], v[166:167], v[168:169], s[50:51] op_sel_hi:[1,1,0]
	v_rcp_f32_e32 v179, v171
	v_pk_fma_f32 v[162:163], v[160:161], v[162:163], s[52:53] op_sel_hi:[1,1,0]
	v_pk_fma_f32 v[168:169], v[166:167], v[168:169], s[52:53] op_sel_hi:[1,1,0]
	v_rcp_f32_e32 v180, v172
	v_pk_fma_f32 v[160:161], v[160:161], v[162:163], s[54:55] op_sel_hi:[1,1,0]
	v_pk_fma_f32 v[166:167], v[166:167], v[168:169], s[54:55] op_sel_hi:[1,1,0]
	v_rcp_f32_e32 v181, v173
	v_pk_fma_f32 v[158:159], v[158:159], v[160:161], 0.5 op_sel_hi:[1,1,0]
	v_pk_fma_f32 v[164:165], v[164:165], v[166:167], 0.5 op_sel_hi:[1,1,0]
	v_pk_mul_f32 v[124:125], v[124:125], v[178:179]
	v_pk_mul_f32 v[128:129], v[128:129], v[158:159]
	v_pk_mul_f32 v[130:131], v[130:131], v[164:165]
	v_pk_mul_f32 v[126:127], v[126:127], v[180:181]
	v_med3_f32 v158, v120, -4.0, 4.0
	v_med3_f32 v164, v122, -4.0, 4.0
	v_pk_mul_f32 v[170:171], v[116:117], v[190:191] op_sel_hi:[1,0]
	v_med3_f32 v159, v121, -4.0, 4.0
	v_med3_f32 v165, v123, -4.0, 4.0
	v_pk_mul_f32 v[172:173], v[118:119], v[190:191] op_sel_hi:[1,0]
	v_pk_mul_f32 v[160:161], v[158:159], v[158:159]
	v_pk_mul_f32 v[166:167], v[164:165], v[164:165]
	v_exp_f32_e32 v170, v170
	v_pk_fma_f32 v[160:161], v[160:161], s[72:73], -1.0 op_sel_hi:[1,0,0]
	v_pk_fma_f32 v[166:167], v[166:167], s[72:73], -1.0 op_sel_hi:[1,0,0]
	v_exp_f32_e32 v171, v171
	v_pk_fma_f32 v[162:163], v[160:161], s[74:75], v[198:199] op_sel_hi:[1,0,0]
	v_pk_fma_f32 v[168:169], v[166:167], s[74:75], v[198:199] op_sel_hi:[1,0,0]
	v_exp_f32_e32 v172, v172
	v_pk_fma_f32 v[162:163], v[160:161], v[162:163], s[2:3] op_sel_hi:[1,1,0]
	v_pk_fma_f32 v[168:169], v[166:167], v[168:169], s[2:3] op_sel_hi:[1,1,0]
	v_exp_f32_e32 v173, v173
	v_pk_fma_f32 v[162:163], v[160:161], v[162:163], s[28:29] op_sel_hi:[1,1,0]
	v_pk_fma_f32 v[168:169], v[166:167], v[168:169], s[28:29] op_sel_hi:[1,1,0]
	v_pk_add_f32 v[170:171], v[170:171], 1.0 op_sel_hi:[1,0]
	v_pk_fma_f32 v[162:163], v[160:161], v[162:163], s[30:31] op_sel_hi:[1,1,0]
	v_pk_fma_f32 v[168:169], v[166:167], v[168:169], s[30:31] op_sel_hi:[1,1,0]
	v_pk_add_f32 v[172:173], v[172:173], 1.0 op_sel_hi:[1,0]
	v_pk_fma_f32 v[162:163], v[160:161], v[162:163], s[48:49] op_sel_hi:[1,1,0]
	v_pk_fma_f32 v[168:169], v[166:167], v[168:169], s[48:49] op_sel_hi:[1,1,0]
	v_rcp_f32_e32 v178, v170
	v_pk_fma_f32 v[162:163], v[160:161], v[162:163], s[50:51] op_sel_hi:[1,1,0]
	v_pk_fma_f32 v[168:169], v[166:167], v[168:169], s[50:51] op_sel_hi:[1,1,0]
	v_rcp_f32_e32 v179, v171
	v_pk_fma_f32 v[162:163], v[160:161], v[162:163], s[52:53] op_sel_hi:[1,1,0]
	v_pk_fma_f32 v[168:169], v[166:167], v[168:169], s[52:53] op_sel_hi:[1,1,0]
	v_rcp_f32_e32 v180, v172
	v_pk_fma_f32 v[160:161], v[160:161], v[162:163], s[54:55] op_sel_hi:[1,1,0]
	v_pk_fma_f32 v[166:167], v[166:167], v[168:169], s[54:55] op_sel_hi:[1,1,0]
	v_rcp_f32_e32 v181, v173
	v_pk_fma_f32 v[158:159], v[158:159], v[160:161], 0.5 op_sel_hi:[1,1,0]
	v_pk_fma_f32 v[164:165], v[164:165], v[166:167], 0.5 op_sel_hi:[1,1,0]
	v_pk_mul_f32 v[116:117], v[116:117], v[178:179]
	v_pk_mul_f32 v[120:121], v[120:121], v[158:159]
	v_pk_mul_f32 v[122:123], v[122:123], v[164:165]
	v_pk_mul_f32 v[118:119], v[118:119], v[180:181]
	v_pk_mul_f32 v[124:125], v[124:125], v[128:129]
	v_pk_mul_f32 v[126:127], v[126:127], v[130:131]
	v_pk_mul_f32 v[116:117], v[116:117], v[120:121]
	v_pk_mul_f32 v[118:119], v[118:119], v[122:123]
	v_cvt_pk_bf16_f32 v128, v124, v125
	v_cvt_pk_bf16_f32 v129, v126, v127
	v_cvt_pk_bf16_f32 v130, v116, v117
	v_cvt_pk_bf16_f32 v131, v118, v119
	global_store_dwordx4 v182, v[128:131], s[10:11]
	v_pk_mul_f32 v[112:113], v[112:113], v[238:239] op_sel_hi:[1,0]
	v_pk_mul_f32 v[114:115], v[114:115], v[238:239] op_sel_hi:[1,0]
	v_pk_mul_f32 v[104:105], v[104:105], v[238:239] op_sel_hi:[1,0]
	v_pk_mul_f32 v[106:107], v[106:107], v[238:239] op_sel_hi:[1,0]
	v_pk_mul_f32 v[108:109], v[108:109], v[238:239] op_sel_hi:[1,0]
	v_pk_mul_f32 v[110:111], v[110:111], v[238:239] op_sel_hi:[1,0]
	v_pk_mul_f32 v[100:101], v[100:101], v[238:239] op_sel_hi:[1,0]
	v_pk_mul_f32 v[102:103], v[102:103], v[238:239] op_sel_hi:[1,0]
	v_med3_f32 v158, v112, -4.0, 4.0
	v_med3_f32 v164, v114, -4.0, 4.0
	v_pk_mul_f32 v[170:171], v[108:109], v[190:191] op_sel_hi:[1,0]
	v_med3_f32 v159, v113, -4.0, 4.0
	v_med3_f32 v165, v115, -4.0, 4.0
	v_pk_mul_f32 v[172:173], v[110:111], v[190:191] op_sel_hi:[1,0]
	v_pk_mul_f32 v[160:161], v[158:159], v[158:159]
	v_pk_mul_f32 v[166:167], v[164:165], v[164:165]
	v_exp_f32_e32 v170, v170
	v_pk_fma_f32 v[160:161], v[160:161], s[72:73], -1.0 op_sel_hi:[1,0,0]
	v_pk_fma_f32 v[166:167], v[166:167], s[72:73], -1.0 op_sel_hi:[1,0,0]
	v_exp_f32_e32 v171, v171
	v_pk_fma_f32 v[162:163], v[160:161], s[74:75], v[198:199] op_sel_hi:[1,0,0]
	v_pk_fma_f32 v[168:169], v[166:167], s[74:75], v[198:199] op_sel_hi:[1,0,0]
	v_exp_f32_e32 v172, v172
	v_pk_fma_f32 v[162:163], v[160:161], v[162:163], s[2:3] op_sel_hi:[1,1,0]
	v_pk_fma_f32 v[168:169], v[166:167], v[168:169], s[2:3] op_sel_hi:[1,1,0]
	v_exp_f32_e32 v173, v173
	v_pk_fma_f32 v[162:163], v[160:161], v[162:163], s[28:29] op_sel_hi:[1,1,0]
	v_pk_fma_f32 v[168:169], v[166:167], v[168:169], s[28:29] op_sel_hi:[1,1,0]
	v_pk_add_f32 v[170:171], v[170:171], 1.0 op_sel_hi:[1,0]
	v_pk_fma_f32 v[162:163], v[160:161], v[162:163], s[30:31] op_sel_hi:[1,1,0]
	v_pk_fma_f32 v[168:169], v[166:167], v[168:169], s[30:31] op_sel_hi:[1,1,0]
	v_pk_add_f32 v[172:173], v[172:173], 1.0 op_sel_hi:[1,0]
	v_pk_fma_f32 v[162:163], v[160:161], v[162:163], s[48:49] op_sel_hi:[1,1,0]
	v_pk_fma_f32 v[168:169], v[166:167], v[168:169], s[48:49] op_sel_hi:[1,1,0]
	v_rcp_f32_e32 v178, v170
	v_pk_fma_f32 v[162:163], v[160:161], v[162:163], s[50:51] op_sel_hi:[1,1,0]
	v_pk_fma_f32 v[168:169], v[166:167], v[168:169], s[50:51] op_sel_hi:[1,1,0]
	v_rcp_f32_e32 v179, v171
	v_pk_fma_f32 v[162:163], v[160:161], v[162:163], s[52:53] op_sel_hi:[1,1,0]
	v_pk_fma_f32 v[168:169], v[166:167], v[168:169], s[52:53] op_sel_hi:[1,1,0]
	v_rcp_f32_e32 v180, v172
	v_pk_fma_f32 v[160:161], v[160:161], v[162:163], s[54:55] op_sel_hi:[1,1,0]
	v_pk_fma_f32 v[166:167], v[166:167], v[168:169], s[54:55] op_sel_hi:[1,1,0]
	v_rcp_f32_e32 v181, v173
	v_pk_fma_f32 v[158:159], v[158:159], v[160:161], 0.5 op_sel_hi:[1,1,0]
	v_pk_fma_f32 v[164:165], v[164:165], v[166:167], 0.5 op_sel_hi:[1,1,0]
	v_pk_mul_f32 v[108:109], v[108:109], v[178:179]
	v_pk_mul_f32 v[112:113], v[112:113], v[158:159]
	v_pk_mul_f32 v[114:115], v[114:115], v[164:165]
	v_pk_mul_f32 v[110:111], v[110:111], v[180:181]
	v_med3_f32 v158, v104, -4.0, 4.0
	v_med3_f32 v164, v106, -4.0, 4.0
	v_pk_mul_f32 v[170:171], v[100:101], v[190:191] op_sel_hi:[1,0]
	v_med3_f32 v159, v105, -4.0, 4.0
	v_med3_f32 v165, v107, -4.0, 4.0
	v_pk_mul_f32 v[172:173], v[102:103], v[190:191] op_sel_hi:[1,0]
	v_pk_mul_f32 v[160:161], v[158:159], v[158:159]
	v_pk_mul_f32 v[166:167], v[164:165], v[164:165]
	v_exp_f32_e32 v170, v170
	v_pk_fma_f32 v[160:161], v[160:161], s[72:73], -1.0 op_sel_hi:[1,0,0]
	v_pk_fma_f32 v[166:167], v[166:167], s[72:73], -1.0 op_sel_hi:[1,0,0]
	v_exp_f32_e32 v171, v171
	v_pk_fma_f32 v[162:163], v[160:161], s[74:75], v[198:199] op_sel_hi:[1,0,0]
	v_pk_fma_f32 v[168:169], v[166:167], s[74:75], v[198:199] op_sel_hi:[1,0,0]
	v_exp_f32_e32 v172, v172
	v_pk_fma_f32 v[162:163], v[160:161], v[162:163], s[2:3] op_sel_hi:[1,1,0]
	v_pk_fma_f32 v[168:169], v[166:167], v[168:169], s[2:3] op_sel_hi:[1,1,0]
	v_exp_f32_e32 v173, v173
	v_pk_fma_f32 v[162:163], v[160:161], v[162:163], s[28:29] op_sel_hi:[1,1,0]
	v_pk_fma_f32 v[168:169], v[166:167], v[168:169], s[28:29] op_sel_hi:[1,1,0]
	v_pk_add_f32 v[170:171], v[170:171], 1.0 op_sel_hi:[1,0]
	v_pk_fma_f32 v[162:163], v[160:161], v[162:163], s[30:31] op_sel_hi:[1,1,0]
	v_pk_fma_f32 v[168:169], v[166:167], v[168:169], s[30:31] op_sel_hi:[1,1,0]
	v_pk_add_f32 v[172:173], v[172:173], 1.0 op_sel_hi:[1,0]
	v_pk_fma_f32 v[162:163], v[160:161], v[162:163], s[48:49] op_sel_hi:[1,1,0]
	v_pk_fma_f32 v[168:169], v[166:167], v[168:169], s[48:49] op_sel_hi:[1,1,0]
	v_rcp_f32_e32 v178, v170
	v_pk_fma_f32 v[162:163], v[160:161], v[162:163], s[50:51] op_sel_hi:[1,1,0]
	v_pk_fma_f32 v[168:169], v[166:167], v[168:169], s[50:51] op_sel_hi:[1,1,0]
	v_rcp_f32_e32 v179, v171
	v_pk_fma_f32 v[162:163], v[160:161], v[162:163], s[52:53] op_sel_hi:[1,1,0]
	v_pk_fma_f32 v[168:169], v[166:167], v[168:169], s[52:53] op_sel_hi:[1,1,0]
	v_rcp_f32_e32 v180, v172
	v_pk_fma_f32 v[160:161], v[160:161], v[162:163], s[54:55] op_sel_hi:[1,1,0]
	v_pk_fma_f32 v[166:167], v[166:167], v[168:169], s[54:55] op_sel_hi:[1,1,0]
	v_rcp_f32_e32 v181, v173
	v_pk_fma_f32 v[158:159], v[158:159], v[160:161], 0.5 op_sel_hi:[1,1,0]
	v_pk_fma_f32 v[164:165], v[164:165], v[166:167], 0.5 op_sel_hi:[1,1,0]
	v_pk_mul_f32 v[100:101], v[100:101], v[178:179]
	v_pk_mul_f32 v[104:105], v[104:105], v[158:159]
	v_pk_mul_f32 v[106:107], v[106:107], v[164:165]
	v_pk_mul_f32 v[102:103], v[102:103], v[180:181]
	v_pk_mul_f32 v[108:109], v[108:109], v[112:113]
	v_pk_mul_f32 v[110:111], v[110:111], v[114:115]
	v_pk_mul_f32 v[100:101], v[100:101], v[104:105]
	v_pk_mul_f32 v[102:103], v[102:103], v[106:107]
	v_cvt_pk_bf16_f32 v112, v108, v109
	v_cvt_pk_bf16_f32 v113, v110, v111
	v_cvt_pk_bf16_f32 v114, v100, v101
	v_cvt_pk_bf16_f32 v115, v102, v103
	global_store_dwordx4 v183, v[112:115], s[10:11]
	v_pk_mul_f32 v[96:97], v[96:97], v[240:241] op_sel_hi:[1,0]
	v_pk_mul_f32 v[98:99], v[98:99], v[240:241] op_sel_hi:[1,0]
	v_pk_mul_f32 v[88:89], v[88:89], v[240:241] op_sel_hi:[1,0]
	v_pk_mul_f32 v[90:91], v[90:91], v[240:241] op_sel_hi:[1,0]
	v_pk_mul_f32 v[92:93], v[92:93], v[240:241] op_sel_hi:[1,0]
	v_pk_mul_f32 v[94:95], v[94:95], v[240:241] op_sel_hi:[1,0]
	v_pk_mul_f32 v[84:85], v[84:85], v[240:241] op_sel_hi:[1,0]
	v_pk_mul_f32 v[86:87], v[86:87], v[240:241] op_sel_hi:[1,0]
	v_med3_f32 v158, v96, -4.0, 4.0
	v_med3_f32 v164, v98, -4.0, 4.0
	v_pk_mul_f32 v[170:171], v[92:93], v[190:191] op_sel_hi:[1,0]
	v_med3_f32 v159, v97, -4.0, 4.0
	v_med3_f32 v165, v99, -4.0, 4.0
	v_pk_mul_f32 v[172:173], v[94:95], v[190:191] op_sel_hi:[1,0]
	v_pk_mul_f32 v[160:161], v[158:159], v[158:159]
	v_pk_mul_f32 v[166:167], v[164:165], v[164:165]
	v_exp_f32_e32 v170, v170
	v_pk_fma_f32 v[160:161], v[160:161], s[72:73], -1.0 op_sel_hi:[1,0,0]
	v_pk_fma_f32 v[166:167], v[166:167], s[72:73], -1.0 op_sel_hi:[1,0,0]
	v_exp_f32_e32 v171, v171
	v_pk_fma_f32 v[162:163], v[160:161], s[74:75], v[198:199] op_sel_hi:[1,0,0]
	v_pk_fma_f32 v[168:169], v[166:167], s[74:75], v[198:199] op_sel_hi:[1,0,0]
	v_exp_f32_e32 v172, v172
	v_pk_fma_f32 v[162:163], v[160:161], v[162:163], s[2:3] op_sel_hi:[1,1,0]
	v_pk_fma_f32 v[168:169], v[166:167], v[168:169], s[2:3] op_sel_hi:[1,1,0]
	v_exp_f32_e32 v173, v173
	v_pk_fma_f32 v[162:163], v[160:161], v[162:163], s[28:29] op_sel_hi:[1,1,0]
	v_pk_fma_f32 v[168:169], v[166:167], v[168:169], s[28:29] op_sel_hi:[1,1,0]
	v_pk_add_f32 v[170:171], v[170:171], 1.0 op_sel_hi:[1,0]
	v_pk_fma_f32 v[162:163], v[160:161], v[162:163], s[30:31] op_sel_hi:[1,1,0]
	v_pk_fma_f32 v[168:169], v[166:167], v[168:169], s[30:31] op_sel_hi:[1,1,0]
	v_pk_add_f32 v[172:173], v[172:173], 1.0 op_sel_hi:[1,0]
	v_pk_fma_f32 v[162:163], v[160:161], v[162:163], s[48:49] op_sel_hi:[1,1,0]
	v_pk_fma_f32 v[168:169], v[166:167], v[168:169], s[48:49] op_sel_hi:[1,1,0]
	v_rcp_f32_e32 v178, v170
	v_pk_fma_f32 v[162:163], v[160:161], v[162:163], s[50:51] op_sel_hi:[1,1,0]
	v_pk_fma_f32 v[168:169], v[166:167], v[168:169], s[50:51] op_sel_hi:[1,1,0]
	v_rcp_f32_e32 v179, v171
	v_pk_fma_f32 v[162:163], v[160:161], v[162:163], s[52:53] op_sel_hi:[1,1,0]
	v_pk_fma_f32 v[168:169], v[166:167], v[168:169], s[52:53] op_sel_hi:[1,1,0]
	v_rcp_f32_e32 v180, v172
	v_pk_fma_f32 v[160:161], v[160:161], v[162:163], s[54:55] op_sel_hi:[1,1,0]
	v_pk_fma_f32 v[166:167], v[166:167], v[168:169], s[54:55] op_sel_hi:[1,1,0]
	v_rcp_f32_e32 v181, v173
	v_pk_fma_f32 v[158:159], v[158:159], v[160:161], 0.5 op_sel_hi:[1,1,0]
	v_pk_fma_f32 v[164:165], v[164:165], v[166:167], 0.5 op_sel_hi:[1,1,0]
	v_pk_mul_f32 v[92:93], v[92:93], v[178:179]
	v_pk_mul_f32 v[96:97], v[96:97], v[158:159]
	v_pk_mul_f32 v[98:99], v[98:99], v[164:165]
	v_pk_mul_f32 v[94:95], v[94:95], v[180:181]
	v_med3_f32 v158, v88, -4.0, 4.0
	v_med3_f32 v164, v90, -4.0, 4.0
	v_pk_mul_f32 v[170:171], v[84:85], v[190:191] op_sel_hi:[1,0]
	v_med3_f32 v159, v89, -4.0, 4.0
	v_med3_f32 v165, v91, -4.0, 4.0
	v_pk_mul_f32 v[172:173], v[86:87], v[190:191] op_sel_hi:[1,0]
	v_pk_mul_f32 v[160:161], v[158:159], v[158:159]
	v_pk_mul_f32 v[166:167], v[164:165], v[164:165]
	v_exp_f32_e32 v170, v170
	v_pk_fma_f32 v[160:161], v[160:161], s[72:73], -1.0 op_sel_hi:[1,0,0]
	v_pk_fma_f32 v[166:167], v[166:167], s[72:73], -1.0 op_sel_hi:[1,0,0]
	v_exp_f32_e32 v171, v171
	v_pk_fma_f32 v[162:163], v[160:161], s[74:75], v[198:199] op_sel_hi:[1,0,0]
	v_pk_fma_f32 v[168:169], v[166:167], s[74:75], v[198:199] op_sel_hi:[1,0,0]
	v_exp_f32_e32 v172, v172
	v_pk_fma_f32 v[162:163], v[160:161], v[162:163], s[2:3] op_sel_hi:[1,1,0]
	v_pk_fma_f32 v[168:169], v[166:167], v[168:169], s[2:3] op_sel_hi:[1,1,0]
	v_exp_f32_e32 v173, v173
	v_pk_fma_f32 v[162:163], v[160:161], v[162:163], s[28:29] op_sel_hi:[1,1,0]
	v_pk_fma_f32 v[168:169], v[166:167], v[168:169], s[28:29] op_sel_hi:[1,1,0]
	v_pk_add_f32 v[170:171], v[170:171], 1.0 op_sel_hi:[1,0]
	v_pk_fma_f32 v[162:163], v[160:161], v[162:163], s[30:31] op_sel_hi:[1,1,0]
	v_pk_fma_f32 v[168:169], v[166:167], v[168:169], s[30:31] op_sel_hi:[1,1,0]
	v_pk_add_f32 v[172:173], v[172:173], 1.0 op_sel_hi:[1,0]
	v_pk_fma_f32 v[162:163], v[160:161], v[162:163], s[48:49] op_sel_hi:[1,1,0]
	v_pk_fma_f32 v[168:169], v[166:167], v[168:169], s[48:49] op_sel_hi:[1,1,0]
	v_rcp_f32_e32 v178, v170
	v_pk_fma_f32 v[162:163], v[160:161], v[162:163], s[50:51] op_sel_hi:[1,1,0]
	v_pk_fma_f32 v[168:169], v[166:167], v[168:169], s[50:51] op_sel_hi:[1,1,0]
	v_rcp_f32_e32 v179, v171
	v_pk_fma_f32 v[162:163], v[160:161], v[162:163], s[52:53] op_sel_hi:[1,1,0]
	v_pk_fma_f32 v[168:169], v[166:167], v[168:169], s[52:53] op_sel_hi:[1,1,0]
	v_rcp_f32_e32 v180, v172
	v_pk_fma_f32 v[160:161], v[160:161], v[162:163], s[54:55] op_sel_hi:[1,1,0]
	v_pk_fma_f32 v[166:167], v[166:167], v[168:169], s[54:55] op_sel_hi:[1,1,0]
	v_rcp_f32_e32 v181, v173
	v_pk_fma_f32 v[158:159], v[158:159], v[160:161], 0.5 op_sel_hi:[1,1,0]
	v_pk_fma_f32 v[164:165], v[164:165], v[166:167], 0.5 op_sel_hi:[1,1,0]
	v_pk_mul_f32 v[84:85], v[84:85], v[178:179]
	v_pk_mul_f32 v[88:89], v[88:89], v[158:159]
	v_pk_mul_f32 v[90:91], v[90:91], v[164:165]
	v_pk_mul_f32 v[86:87], v[86:87], v[180:181]
	v_pk_mul_f32 v[92:93], v[92:93], v[96:97]
	v_pk_mul_f32 v[94:95], v[94:95], v[98:99]
	v_pk_mul_f32 v[84:85], v[84:85], v[88:89]
	v_pk_mul_f32 v[86:87], v[86:87], v[90:91]
	v_cvt_pk_bf16_f32 v96, v92, v93
	v_cvt_pk_bf16_f32 v97, v94, v95
	v_cvt_pk_bf16_f32 v98, v84, v85
	v_cvt_pk_bf16_f32 v99, v86, v87
	global_store_dwordx4 v184, v[96:99], s[10:11]
	v_pk_mul_f32 v[80:81], v[80:81], v[242:243] op_sel_hi:[1,0]
	v_pk_mul_f32 v[82:83], v[82:83], v[242:243] op_sel_hi:[1,0]
	v_pk_mul_f32 v[72:73], v[72:73], v[242:243] op_sel_hi:[1,0]
	v_pk_mul_f32 v[74:75], v[74:75], v[242:243] op_sel_hi:[1,0]
	v_pk_mul_f32 v[76:77], v[76:77], v[242:243] op_sel_hi:[1,0]
	v_pk_mul_f32 v[78:79], v[78:79], v[242:243] op_sel_hi:[1,0]
	v_pk_mul_f32 v[68:69], v[68:69], v[242:243] op_sel_hi:[1,0]
	v_pk_mul_f32 v[70:71], v[70:71], v[242:243] op_sel_hi:[1,0]
	v_med3_f32 v158, v80, -4.0, 4.0
	v_med3_f32 v164, v82, -4.0, 4.0
	v_pk_mul_f32 v[170:171], v[76:77], v[190:191] op_sel_hi:[1,0]
	v_med3_f32 v159, v81, -4.0, 4.0
	v_med3_f32 v165, v83, -4.0, 4.0
	v_pk_mul_f32 v[172:173], v[78:79], v[190:191] op_sel_hi:[1,0]
	v_pk_mul_f32 v[160:161], v[158:159], v[158:159]
	v_pk_mul_f32 v[166:167], v[164:165], v[164:165]
	v_exp_f32_e32 v170, v170
	v_pk_fma_f32 v[160:161], v[160:161], s[72:73], -1.0 op_sel_hi:[1,0,0]
	v_pk_fma_f32 v[166:167], v[166:167], s[72:73], -1.0 op_sel_hi:[1,0,0]
	v_exp_f32_e32 v171, v171
	v_pk_fma_f32 v[162:163], v[160:161], s[74:75], v[198:199] op_sel_hi:[1,0,0]
	v_pk_fma_f32 v[168:169], v[166:167], s[74:75], v[198:199] op_sel_hi:[1,0,0]
	v_exp_f32_e32 v172, v172
	v_pk_fma_f32 v[162:163], v[160:161], v[162:163], s[2:3] op_sel_hi:[1,1,0]
	v_pk_fma_f32 v[168:169], v[166:167], v[168:169], s[2:3] op_sel_hi:[1,1,0]
	v_exp_f32_e32 v173, v173
	v_pk_fma_f32 v[162:163], v[160:161], v[162:163], s[28:29] op_sel_hi:[1,1,0]
	v_pk_fma_f32 v[168:169], v[166:167], v[168:169], s[28:29] op_sel_hi:[1,1,0]
	v_pk_add_f32 v[170:171], v[170:171], 1.0 op_sel_hi:[1,0]
	v_pk_fma_f32 v[162:163], v[160:161], v[162:163], s[30:31] op_sel_hi:[1,1,0]
	v_pk_fma_f32 v[168:169], v[166:167], v[168:169], s[30:31] op_sel_hi:[1,1,0]
	v_pk_add_f32 v[172:173], v[172:173], 1.0 op_sel_hi:[1,0]
	v_pk_fma_f32 v[162:163], v[160:161], v[162:163], s[48:49] op_sel_hi:[1,1,0]
	v_pk_fma_f32 v[168:169], v[166:167], v[168:169], s[48:49] op_sel_hi:[1,1,0]
	v_rcp_f32_e32 v178, v170
	v_pk_fma_f32 v[162:163], v[160:161], v[162:163], s[50:51] op_sel_hi:[1,1,0]
	v_pk_fma_f32 v[168:169], v[166:167], v[168:169], s[50:51] op_sel_hi:[1,1,0]
	v_rcp_f32_e32 v179, v171
	v_pk_fma_f32 v[162:163], v[160:161], v[162:163], s[52:53] op_sel_hi:[1,1,0]
	v_pk_fma_f32 v[168:169], v[166:167], v[168:169], s[52:53] op_sel_hi:[1,1,0]
	v_rcp_f32_e32 v180, v172
	v_pk_fma_f32 v[160:161], v[160:161], v[162:163], s[54:55] op_sel_hi:[1,1,0]
	v_pk_fma_f32 v[166:167], v[166:167], v[168:169], s[54:55] op_sel_hi:[1,1,0]
	v_rcp_f32_e32 v181, v173
	v_pk_fma_f32 v[158:159], v[158:159], v[160:161], 0.5 op_sel_hi:[1,1,0]
	v_pk_fma_f32 v[164:165], v[164:165], v[166:167], 0.5 op_sel_hi:[1,1,0]
	v_pk_mul_f32 v[76:77], v[76:77], v[178:179]
	v_pk_mul_f32 v[80:81], v[80:81], v[158:159]
	v_pk_mul_f32 v[82:83], v[82:83], v[164:165]
	v_pk_mul_f32 v[78:79], v[78:79], v[180:181]
	v_med3_f32 v158, v72, -4.0, 4.0
	v_med3_f32 v164, v74, -4.0, 4.0
	v_pk_mul_f32 v[170:171], v[68:69], v[190:191] op_sel_hi:[1,0]
	v_med3_f32 v159, v73, -4.0, 4.0
	v_med3_f32 v165, v75, -4.0, 4.0
	v_pk_mul_f32 v[172:173], v[70:71], v[190:191] op_sel_hi:[1,0]
	v_pk_mul_f32 v[160:161], v[158:159], v[158:159]
	v_pk_mul_f32 v[166:167], v[164:165], v[164:165]
	v_exp_f32_e32 v170, v170
	v_pk_fma_f32 v[160:161], v[160:161], s[72:73], -1.0 op_sel_hi:[1,0,0]
	v_pk_fma_f32 v[166:167], v[166:167], s[72:73], -1.0 op_sel_hi:[1,0,0]
	v_exp_f32_e32 v171, v171
	v_pk_fma_f32 v[162:163], v[160:161], s[74:75], v[198:199] op_sel_hi:[1,0,0]
	v_pk_fma_f32 v[168:169], v[166:167], s[74:75], v[198:199] op_sel_hi:[1,0,0]
	v_exp_f32_e32 v172, v172
	v_pk_fma_f32 v[162:163], v[160:161], v[162:163], s[2:3] op_sel_hi:[1,1,0]
	v_pk_fma_f32 v[168:169], v[166:167], v[168:169], s[2:3] op_sel_hi:[1,1,0]
	v_exp_f32_e32 v173, v173
	v_pk_fma_f32 v[162:163], v[160:161], v[162:163], s[28:29] op_sel_hi:[1,1,0]
	v_pk_fma_f32 v[168:169], v[166:167], v[168:169], s[28:29] op_sel_hi:[1,1,0]
	v_pk_add_f32 v[170:171], v[170:171], 1.0 op_sel_hi:[1,0]
	v_pk_fma_f32 v[162:163], v[160:161], v[162:163], s[30:31] op_sel_hi:[1,1,0]
	v_pk_fma_f32 v[168:169], v[166:167], v[168:169], s[30:31] op_sel_hi:[1,1,0]
	v_pk_add_f32 v[172:173], v[172:173], 1.0 op_sel_hi:[1,0]
	v_pk_fma_f32 v[162:163], v[160:161], v[162:163], s[48:49] op_sel_hi:[1,1,0]
	v_pk_fma_f32 v[168:169], v[166:167], v[168:169], s[48:49] op_sel_hi:[1,1,0]
	v_rcp_f32_e32 v178, v170
	v_pk_fma_f32 v[162:163], v[160:161], v[162:163], s[50:51] op_sel_hi:[1,1,0]
	v_pk_fma_f32 v[168:169], v[166:167], v[168:169], s[50:51] op_sel_hi:[1,1,0]
	v_rcp_f32_e32 v179, v171
	v_pk_fma_f32 v[162:163], v[160:161], v[162:163], s[52:53] op_sel_hi:[1,1,0]
	v_pk_fma_f32 v[168:169], v[166:167], v[168:169], s[52:53] op_sel_hi:[1,1,0]
	v_rcp_f32_e32 v180, v172
	v_pk_fma_f32 v[160:161], v[160:161], v[162:163], s[54:55] op_sel_hi:[1,1,0]
	v_pk_fma_f32 v[166:167], v[166:167], v[168:169], s[54:55] op_sel_hi:[1,1,0]
	v_rcp_f32_e32 v181, v173
	v_pk_fma_f32 v[158:159], v[158:159], v[160:161], 0.5 op_sel_hi:[1,1,0]
	v_pk_fma_f32 v[164:165], v[164:165], v[166:167], 0.5 op_sel_hi:[1,1,0]
	v_pk_mul_f32 v[68:69], v[68:69], v[178:179]
	v_pk_mul_f32 v[72:73], v[72:73], v[158:159]
	v_pk_mul_f32 v[74:75], v[74:75], v[164:165]
	v_pk_mul_f32 v[70:71], v[70:71], v[180:181]
	v_pk_mul_f32 v[76:77], v[76:77], v[80:81]
	v_pk_mul_f32 v[78:79], v[78:79], v[82:83]
	v_pk_mul_f32 v[68:69], v[68:69], v[72:73]
	v_pk_mul_f32 v[70:71], v[70:71], v[74:75]
	v_cvt_pk_bf16_f32 v80, v76, v77
	v_cvt_pk_bf16_f32 v81, v78, v79
	v_cvt_pk_bf16_f32 v82, v68, v69
	v_cvt_pk_bf16_f32 v83, v70, v71
	global_store_dwordx4 v185, v[80:83], s[10:11]
	v_pk_mul_f32 v[64:65], v[64:65], v[244:245] op_sel_hi:[1,0]
	v_pk_mul_f32 v[66:67], v[66:67], v[244:245] op_sel_hi:[1,0]
	v_pk_mul_f32 v[56:57], v[56:57], v[244:245] op_sel_hi:[1,0]
	v_pk_mul_f32 v[58:59], v[58:59], v[244:245] op_sel_hi:[1,0]
	v_pk_mul_f32 v[60:61], v[60:61], v[244:245] op_sel_hi:[1,0]
	v_pk_mul_f32 v[62:63], v[62:63], v[244:245] op_sel_hi:[1,0]
	v_pk_mul_f32 v[52:53], v[52:53], v[244:245] op_sel_hi:[1,0]
	v_pk_mul_f32 v[54:55], v[54:55], v[244:245] op_sel_hi:[1,0]
	v_med3_f32 v158, v64, -4.0, 4.0
	v_med3_f32 v164, v66, -4.0, 4.0
	v_pk_mul_f32 v[170:171], v[60:61], v[190:191] op_sel_hi:[1,0]
	v_med3_f32 v159, v65, -4.0, 4.0
	v_med3_f32 v165, v67, -4.0, 4.0
	v_pk_mul_f32 v[172:173], v[62:63], v[190:191] op_sel_hi:[1,0]
	v_pk_mul_f32 v[160:161], v[158:159], v[158:159]
	v_pk_mul_f32 v[166:167], v[164:165], v[164:165]
	v_exp_f32_e32 v170, v170
	v_pk_fma_f32 v[160:161], v[160:161], s[72:73], -1.0 op_sel_hi:[1,0,0]
	v_pk_fma_f32 v[166:167], v[166:167], s[72:73], -1.0 op_sel_hi:[1,0,0]
	v_exp_f32_e32 v171, v171
	v_pk_fma_f32 v[162:163], v[160:161], s[74:75], v[198:199] op_sel_hi:[1,0,0]
	v_pk_fma_f32 v[168:169], v[166:167], s[74:75], v[198:199] op_sel_hi:[1,0,0]
	v_exp_f32_e32 v172, v172
	v_pk_fma_f32 v[162:163], v[160:161], v[162:163], s[2:3] op_sel_hi:[1,1,0]
	v_pk_fma_f32 v[168:169], v[166:167], v[168:169], s[2:3] op_sel_hi:[1,1,0]
	v_exp_f32_e32 v173, v173
	v_pk_fma_f32 v[162:163], v[160:161], v[162:163], s[28:29] op_sel_hi:[1,1,0]
	v_pk_fma_f32 v[168:169], v[166:167], v[168:169], s[28:29] op_sel_hi:[1,1,0]
	v_pk_add_f32 v[170:171], v[170:171], 1.0 op_sel_hi:[1,0]
	v_pk_fma_f32 v[162:163], v[160:161], v[162:163], s[30:31] op_sel_hi:[1,1,0]
	v_pk_fma_f32 v[168:169], v[166:167], v[168:169], s[30:31] op_sel_hi:[1,1,0]
	v_pk_add_f32 v[172:173], v[172:173], 1.0 op_sel_hi:[1,0]
	v_pk_fma_f32 v[162:163], v[160:161], v[162:163], s[48:49] op_sel_hi:[1,1,0]
	v_pk_fma_f32 v[168:169], v[166:167], v[168:169], s[48:49] op_sel_hi:[1,1,0]
	v_rcp_f32_e32 v178, v170
	v_pk_fma_f32 v[162:163], v[160:161], v[162:163], s[50:51] op_sel_hi:[1,1,0]
	v_pk_fma_f32 v[168:169], v[166:167], v[168:169], s[50:51] op_sel_hi:[1,1,0]
	v_rcp_f32_e32 v179, v171
	v_pk_fma_f32 v[162:163], v[160:161], v[162:163], s[52:53] op_sel_hi:[1,1,0]
	v_pk_fma_f32 v[168:169], v[166:167], v[168:169], s[52:53] op_sel_hi:[1,1,0]
	v_rcp_f32_e32 v180, v172
	v_pk_fma_f32 v[160:161], v[160:161], v[162:163], s[54:55] op_sel_hi:[1,1,0]
	v_pk_fma_f32 v[166:167], v[166:167], v[168:169], s[54:55] op_sel_hi:[1,1,0]
	v_rcp_f32_e32 v181, v173
	v_pk_fma_f32 v[158:159], v[158:159], v[160:161], 0.5 op_sel_hi:[1,1,0]
	v_pk_fma_f32 v[164:165], v[164:165], v[166:167], 0.5 op_sel_hi:[1,1,0]
	v_pk_mul_f32 v[60:61], v[60:61], v[178:179]
	v_pk_mul_f32 v[64:65], v[64:65], v[158:159]
	v_pk_mul_f32 v[66:67], v[66:67], v[164:165]
	v_pk_mul_f32 v[62:63], v[62:63], v[180:181]
	v_med3_f32 v158, v56, -4.0, 4.0
	v_med3_f32 v164, v58, -4.0, 4.0
	v_pk_mul_f32 v[170:171], v[52:53], v[190:191] op_sel_hi:[1,0]
	v_med3_f32 v159, v57, -4.0, 4.0
	v_med3_f32 v165, v59, -4.0, 4.0
	v_pk_mul_f32 v[172:173], v[54:55], v[190:191] op_sel_hi:[1,0]
	v_pk_mul_f32 v[160:161], v[158:159], v[158:159]
	v_pk_mul_f32 v[166:167], v[164:165], v[164:165]
	v_exp_f32_e32 v170, v170
	v_pk_fma_f32 v[160:161], v[160:161], s[72:73], -1.0 op_sel_hi:[1,0,0]
	v_pk_fma_f32 v[166:167], v[166:167], s[72:73], -1.0 op_sel_hi:[1,0,0]
	v_exp_f32_e32 v171, v171
	v_pk_fma_f32 v[162:163], v[160:161], s[74:75], v[198:199] op_sel_hi:[1,0,0]
	v_pk_fma_f32 v[168:169], v[166:167], s[74:75], v[198:199] op_sel_hi:[1,0,0]
	v_exp_f32_e32 v172, v172
	v_pk_fma_f32 v[162:163], v[160:161], v[162:163], s[2:3] op_sel_hi:[1,1,0]
	v_pk_fma_f32 v[168:169], v[166:167], v[168:169], s[2:3] op_sel_hi:[1,1,0]
	v_exp_f32_e32 v173, v173
	v_pk_fma_f32 v[162:163], v[160:161], v[162:163], s[28:29] op_sel_hi:[1,1,0]
	v_pk_fma_f32 v[168:169], v[166:167], v[168:169], s[28:29] op_sel_hi:[1,1,0]
	v_pk_add_f32 v[170:171], v[170:171], 1.0 op_sel_hi:[1,0]
	v_pk_fma_f32 v[162:163], v[160:161], v[162:163], s[30:31] op_sel_hi:[1,1,0]
	v_pk_fma_f32 v[168:169], v[166:167], v[168:169], s[30:31] op_sel_hi:[1,1,0]
	v_pk_add_f32 v[172:173], v[172:173], 1.0 op_sel_hi:[1,0]
	v_pk_fma_f32 v[162:163], v[160:161], v[162:163], s[48:49] op_sel_hi:[1,1,0]
	v_pk_fma_f32 v[168:169], v[166:167], v[168:169], s[48:49] op_sel_hi:[1,1,0]
	v_rcp_f32_e32 v178, v170
	v_pk_fma_f32 v[162:163], v[160:161], v[162:163], s[50:51] op_sel_hi:[1,1,0]
	v_pk_fma_f32 v[168:169], v[166:167], v[168:169], s[50:51] op_sel_hi:[1,1,0]
	v_rcp_f32_e32 v179, v171
	v_pk_fma_f32 v[162:163], v[160:161], v[162:163], s[52:53] op_sel_hi:[1,1,0]
	v_pk_fma_f32 v[168:169], v[166:167], v[168:169], s[52:53] op_sel_hi:[1,1,0]
	v_rcp_f32_e32 v180, v172
	v_pk_fma_f32 v[160:161], v[160:161], v[162:163], s[54:55] op_sel_hi:[1,1,0]
	v_pk_fma_f32 v[166:167], v[166:167], v[168:169], s[54:55] op_sel_hi:[1,1,0]
	v_rcp_f32_e32 v181, v173
	v_pk_fma_f32 v[158:159], v[158:159], v[160:161], 0.5 op_sel_hi:[1,1,0]
	v_pk_fma_f32 v[164:165], v[164:165], v[166:167], 0.5 op_sel_hi:[1,1,0]
	v_pk_mul_f32 v[52:53], v[52:53], v[178:179]
	v_pk_mul_f32 v[56:57], v[56:57], v[158:159]
	v_pk_mul_f32 v[58:59], v[58:59], v[164:165]
	v_pk_mul_f32 v[54:55], v[54:55], v[180:181]
	v_pk_mul_f32 v[60:61], v[60:61], v[64:65]
	v_pk_mul_f32 v[62:63], v[62:63], v[66:67]
	v_pk_mul_f32 v[52:53], v[52:53], v[56:57]
	v_pk_mul_f32 v[54:55], v[54:55], v[58:59]
	v_cvt_pk_bf16_f32 v64, v60, v61
	v_cvt_pk_bf16_f32 v65, v62, v63
	v_cvt_pk_bf16_f32 v66, v52, v53
	v_cvt_pk_bf16_f32 v67, v54, v55
	global_store_dwordx4 v186, v[64:67], s[10:11]
	v_pk_mul_f32 v[48:49], v[48:49], v[246:247] op_sel_hi:[1,0]
	v_pk_mul_f32 v[50:51], v[50:51], v[246:247] op_sel_hi:[1,0]
	v_pk_mul_f32 v[40:41], v[40:41], v[246:247] op_sel_hi:[1,0]
	v_pk_mul_f32 v[42:43], v[42:43], v[246:247] op_sel_hi:[1,0]
	v_pk_mul_f32 v[44:45], v[44:45], v[246:247] op_sel_hi:[1,0]
	v_pk_mul_f32 v[46:47], v[46:47], v[246:247] op_sel_hi:[1,0]
	v_pk_mul_f32 v[36:37], v[36:37], v[246:247] op_sel_hi:[1,0]
	v_pk_mul_f32 v[38:39], v[38:39], v[246:247] op_sel_hi:[1,0]
	v_med3_f32 v158, v48, -4.0, 4.0
	v_med3_f32 v164, v50, -4.0, 4.0
	v_pk_mul_f32 v[170:171], v[44:45], v[190:191] op_sel_hi:[1,0]
	v_med3_f32 v159, v49, -4.0, 4.0
	v_med3_f32 v165, v51, -4.0, 4.0
	v_pk_mul_f32 v[172:173], v[46:47], v[190:191] op_sel_hi:[1,0]
	v_pk_mul_f32 v[160:161], v[158:159], v[158:159]
	v_pk_mul_f32 v[166:167], v[164:165], v[164:165]
	v_exp_f32_e32 v170, v170
	v_pk_fma_f32 v[160:161], v[160:161], s[72:73], -1.0 op_sel_hi:[1,0,0]
	v_pk_fma_f32 v[166:167], v[166:167], s[72:73], -1.0 op_sel_hi:[1,0,0]
	v_exp_f32_e32 v171, v171
	v_pk_fma_f32 v[162:163], v[160:161], s[74:75], v[198:199] op_sel_hi:[1,0,0]
	v_pk_fma_f32 v[168:169], v[166:167], s[74:75], v[198:199] op_sel_hi:[1,0,0]
	v_exp_f32_e32 v172, v172
	v_pk_fma_f32 v[162:163], v[160:161], v[162:163], s[2:3] op_sel_hi:[1,1,0]
	v_pk_fma_f32 v[168:169], v[166:167], v[168:169], s[2:3] op_sel_hi:[1,1,0]
	v_exp_f32_e32 v173, v173
	v_pk_fma_f32 v[162:163], v[160:161], v[162:163], s[28:29] op_sel_hi:[1,1,0]
	v_pk_fma_f32 v[168:169], v[166:167], v[168:169], s[28:29] op_sel_hi:[1,1,0]
	v_pk_add_f32 v[170:171], v[170:171], 1.0 op_sel_hi:[1,0]
	v_pk_fma_f32 v[162:163], v[160:161], v[162:163], s[30:31] op_sel_hi:[1,1,0]
	v_pk_fma_f32 v[168:169], v[166:167], v[168:169], s[30:31] op_sel_hi:[1,1,0]
	v_pk_add_f32 v[172:173], v[172:173], 1.0 op_sel_hi:[1,0]
	v_pk_fma_f32 v[162:163], v[160:161], v[162:163], s[48:49] op_sel_hi:[1,1,0]
	v_pk_fma_f32 v[168:169], v[166:167], v[168:169], s[48:49] op_sel_hi:[1,1,0]
	v_rcp_f32_e32 v178, v170
	v_pk_fma_f32 v[162:163], v[160:161], v[162:163], s[50:51] op_sel_hi:[1,1,0]
	v_pk_fma_f32 v[168:169], v[166:167], v[168:169], s[50:51] op_sel_hi:[1,1,0]
	v_rcp_f32_e32 v179, v171
	v_pk_fma_f32 v[162:163], v[160:161], v[162:163], s[52:53] op_sel_hi:[1,1,0]
	v_pk_fma_f32 v[168:169], v[166:167], v[168:169], s[52:53] op_sel_hi:[1,1,0]
	v_rcp_f32_e32 v180, v172
	v_pk_fma_f32 v[160:161], v[160:161], v[162:163], s[54:55] op_sel_hi:[1,1,0]
	v_pk_fma_f32 v[166:167], v[166:167], v[168:169], s[54:55] op_sel_hi:[1,1,0]
	v_rcp_f32_e32 v181, v173
	v_pk_fma_f32 v[158:159], v[158:159], v[160:161], 0.5 op_sel_hi:[1,1,0]
	v_pk_fma_f32 v[164:165], v[164:165], v[166:167], 0.5 op_sel_hi:[1,1,0]
	v_pk_mul_f32 v[44:45], v[44:45], v[178:179]
	v_pk_mul_f32 v[48:49], v[48:49], v[158:159]
	v_pk_mul_f32 v[50:51], v[50:51], v[164:165]
	v_pk_mul_f32 v[46:47], v[46:47], v[180:181]
	v_med3_f32 v158, v40, -4.0, 4.0
	v_med3_f32 v164, v42, -4.0, 4.0
	v_pk_mul_f32 v[170:171], v[36:37], v[190:191] op_sel_hi:[1,0]
	v_med3_f32 v159, v41, -4.0, 4.0
	v_med3_f32 v165, v43, -4.0, 4.0
	v_pk_mul_f32 v[172:173], v[38:39], v[190:191] op_sel_hi:[1,0]
	v_pk_mul_f32 v[160:161], v[158:159], v[158:159]
	v_pk_mul_f32 v[166:167], v[164:165], v[164:165]
	v_exp_f32_e32 v170, v170
	v_pk_fma_f32 v[160:161], v[160:161], s[72:73], -1.0 op_sel_hi:[1,0,0]
	v_pk_fma_f32 v[166:167], v[166:167], s[72:73], -1.0 op_sel_hi:[1,0,0]
	v_exp_f32_e32 v171, v171
	v_pk_fma_f32 v[162:163], v[160:161], s[74:75], v[198:199] op_sel_hi:[1,0,0]
	v_pk_fma_f32 v[168:169], v[166:167], s[74:75], v[198:199] op_sel_hi:[1,0,0]
	v_exp_f32_e32 v172, v172
	v_pk_fma_f32 v[162:163], v[160:161], v[162:163], s[2:3] op_sel_hi:[1,1,0]
	v_pk_fma_f32 v[168:169], v[166:167], v[168:169], s[2:3] op_sel_hi:[1,1,0]
	v_exp_f32_e32 v173, v173
	v_pk_fma_f32 v[162:163], v[160:161], v[162:163], s[28:29] op_sel_hi:[1,1,0]
	v_pk_fma_f32 v[168:169], v[166:167], v[168:169], s[28:29] op_sel_hi:[1,1,0]
	v_pk_add_f32 v[170:171], v[170:171], 1.0 op_sel_hi:[1,0]
	v_pk_fma_f32 v[162:163], v[160:161], v[162:163], s[30:31] op_sel_hi:[1,1,0]
	v_pk_fma_f32 v[168:169], v[166:167], v[168:169], s[30:31] op_sel_hi:[1,1,0]
	v_pk_add_f32 v[172:173], v[172:173], 1.0 op_sel_hi:[1,0]
	v_pk_fma_f32 v[162:163], v[160:161], v[162:163], s[48:49] op_sel_hi:[1,1,0]
	v_pk_fma_f32 v[168:169], v[166:167], v[168:169], s[48:49] op_sel_hi:[1,1,0]
	v_rcp_f32_e32 v178, v170
	v_pk_fma_f32 v[162:163], v[160:161], v[162:163], s[50:51] op_sel_hi:[1,1,0]
	v_pk_fma_f32 v[168:169], v[166:167], v[168:169], s[50:51] op_sel_hi:[1,1,0]
	v_rcp_f32_e32 v179, v171
	v_pk_fma_f32 v[162:163], v[160:161], v[162:163], s[52:53] op_sel_hi:[1,1,0]
	v_pk_fma_f32 v[168:169], v[166:167], v[168:169], s[52:53] op_sel_hi:[1,1,0]
	v_rcp_f32_e32 v180, v172
	v_pk_fma_f32 v[160:161], v[160:161], v[162:163], s[54:55] op_sel_hi:[1,1,0]
	v_pk_fma_f32 v[166:167], v[166:167], v[168:169], s[54:55] op_sel_hi:[1,1,0]
	v_rcp_f32_e32 v181, v173
	v_pk_fma_f32 v[158:159], v[158:159], v[160:161], 0.5 op_sel_hi:[1,1,0]
	v_pk_fma_f32 v[164:165], v[164:165], v[166:167], 0.5 op_sel_hi:[1,1,0]
	v_pk_mul_f32 v[36:37], v[36:37], v[178:179]
	v_pk_mul_f32 v[40:41], v[40:41], v[158:159]
	v_pk_mul_f32 v[42:43], v[42:43], v[164:165]
	v_pk_mul_f32 v[38:39], v[38:39], v[180:181]
	v_pk_mul_f32 v[44:45], v[44:45], v[48:49]
	v_pk_mul_f32 v[46:47], v[46:47], v[50:51]
	v_pk_mul_f32 v[36:37], v[36:37], v[40:41]
	v_pk_mul_f32 v[38:39], v[38:39], v[42:43]
	v_cvt_pk_bf16_f32 v48, v44, v45
	v_cvt_pk_bf16_f32 v49, v46, v47
	v_cvt_pk_bf16_f32 v50, v36, v37
	v_cvt_pk_bf16_f32 v51, v38, v39
	global_store_dwordx4 v187, v[48:51], s[10:11]
	v_pk_mul_f32 v[32:33], v[32:33], v[248:249] op_sel_hi:[1,0]
	v_pk_mul_f32 v[34:35], v[34:35], v[248:249] op_sel_hi:[1,0]
	v_pk_mul_f32 v[24:25], v[24:25], v[248:249] op_sel_hi:[1,0]
	v_pk_mul_f32 v[26:27], v[26:27], v[248:249] op_sel_hi:[1,0]
	v_pk_mul_f32 v[28:29], v[28:29], v[248:249] op_sel_hi:[1,0]
	v_pk_mul_f32 v[30:31], v[30:31], v[248:249] op_sel_hi:[1,0]
	v_pk_mul_f32 v[20:21], v[20:21], v[248:249] op_sel_hi:[1,0]
	v_pk_mul_f32 v[22:23], v[22:23], v[248:249] op_sel_hi:[1,0]
	v_med3_f32 v158, v32, -4.0, 4.0
	v_med3_f32 v164, v34, -4.0, 4.0
	v_pk_mul_f32 v[170:171], v[28:29], v[190:191] op_sel_hi:[1,0]
	v_med3_f32 v159, v33, -4.0, 4.0
	v_med3_f32 v165, v35, -4.0, 4.0
	v_pk_mul_f32 v[172:173], v[30:31], v[190:191] op_sel_hi:[1,0]
	v_pk_mul_f32 v[160:161], v[158:159], v[158:159]
	v_pk_mul_f32 v[166:167], v[164:165], v[164:165]
	v_exp_f32_e32 v170, v170
	v_pk_fma_f32 v[160:161], v[160:161], s[72:73], -1.0 op_sel_hi:[1,0,0]
	v_pk_fma_f32 v[166:167], v[166:167], s[72:73], -1.0 op_sel_hi:[1,0,0]
	v_exp_f32_e32 v171, v171
	v_pk_fma_f32 v[162:163], v[160:161], s[74:75], v[198:199] op_sel_hi:[1,0,0]
	v_pk_fma_f32 v[168:169], v[166:167], s[74:75], v[198:199] op_sel_hi:[1,0,0]
	v_exp_f32_e32 v172, v172
	v_pk_fma_f32 v[162:163], v[160:161], v[162:163], s[2:3] op_sel_hi:[1,1,0]
	v_pk_fma_f32 v[168:169], v[166:167], v[168:169], s[2:3] op_sel_hi:[1,1,0]
	v_exp_f32_e32 v173, v173
	v_pk_fma_f32 v[162:163], v[160:161], v[162:163], s[28:29] op_sel_hi:[1,1,0]
	v_pk_fma_f32 v[168:169], v[166:167], v[168:169], s[28:29] op_sel_hi:[1,1,0]
	v_pk_add_f32 v[170:171], v[170:171], 1.0 op_sel_hi:[1,0]
	v_pk_fma_f32 v[162:163], v[160:161], v[162:163], s[30:31] op_sel_hi:[1,1,0]
	v_pk_fma_f32 v[168:169], v[166:167], v[168:169], s[30:31] op_sel_hi:[1,1,0]
	v_pk_add_f32 v[172:173], v[172:173], 1.0 op_sel_hi:[1,0]
	v_pk_fma_f32 v[162:163], v[160:161], v[162:163], s[48:49] op_sel_hi:[1,1,0]
	v_pk_fma_f32 v[168:169], v[166:167], v[168:169], s[48:49] op_sel_hi:[1,1,0]
	v_rcp_f32_e32 v178, v170
	v_pk_fma_f32 v[162:163], v[160:161], v[162:163], s[50:51] op_sel_hi:[1,1,0]
	v_pk_fma_f32 v[168:169], v[166:167], v[168:169], s[50:51] op_sel_hi:[1,1,0]
	v_rcp_f32_e32 v179, v171
	v_pk_fma_f32 v[162:163], v[160:161], v[162:163], s[52:53] op_sel_hi:[1,1,0]
	v_pk_fma_f32 v[168:169], v[166:167], v[168:169], s[52:53] op_sel_hi:[1,1,0]
	v_rcp_f32_e32 v180, v172
	v_pk_fma_f32 v[160:161], v[160:161], v[162:163], s[54:55] op_sel_hi:[1,1,0]
	v_pk_fma_f32 v[166:167], v[166:167], v[168:169], s[54:55] op_sel_hi:[1,1,0]
	v_rcp_f32_e32 v181, v173
	v_pk_fma_f32 v[158:159], v[158:159], v[160:161], 0.5 op_sel_hi:[1,1,0]
	v_pk_fma_f32 v[164:165], v[164:165], v[166:167], 0.5 op_sel_hi:[1,1,0]
	v_pk_mul_f32 v[28:29], v[28:29], v[178:179]
	v_pk_mul_f32 v[32:33], v[32:33], v[158:159]
	v_pk_mul_f32 v[34:35], v[34:35], v[164:165]
	v_pk_mul_f32 v[30:31], v[30:31], v[180:181]
	v_med3_f32 v158, v24, -4.0, 4.0
	v_med3_f32 v164, v26, -4.0, 4.0
	v_pk_mul_f32 v[170:171], v[20:21], v[190:191] op_sel_hi:[1,0]
	v_med3_f32 v159, v25, -4.0, 4.0
	v_med3_f32 v165, v27, -4.0, 4.0
	v_pk_mul_f32 v[172:173], v[22:23], v[190:191] op_sel_hi:[1,0]
	v_pk_mul_f32 v[160:161], v[158:159], v[158:159]
	v_pk_mul_f32 v[166:167], v[164:165], v[164:165]
	v_exp_f32_e32 v170, v170
	v_pk_fma_f32 v[160:161], v[160:161], s[72:73], -1.0 op_sel_hi:[1,0,0]
	v_pk_fma_f32 v[166:167], v[166:167], s[72:73], -1.0 op_sel_hi:[1,0,0]
	v_exp_f32_e32 v171, v171
	v_pk_fma_f32 v[162:163], v[160:161], s[74:75], v[198:199] op_sel_hi:[1,0,0]
	v_pk_fma_f32 v[168:169], v[166:167], s[74:75], v[198:199] op_sel_hi:[1,0,0]
	v_exp_f32_e32 v172, v172
	v_pk_fma_f32 v[162:163], v[160:161], v[162:163], s[2:3] op_sel_hi:[1,1,0]
	v_pk_fma_f32 v[168:169], v[166:167], v[168:169], s[2:3] op_sel_hi:[1,1,0]
	v_exp_f32_e32 v173, v173
	v_pk_fma_f32 v[162:163], v[160:161], v[162:163], s[28:29] op_sel_hi:[1,1,0]
	v_pk_fma_f32 v[168:169], v[166:167], v[168:169], s[28:29] op_sel_hi:[1,1,0]
	v_pk_add_f32 v[170:171], v[170:171], 1.0 op_sel_hi:[1,0]
	v_pk_fma_f32 v[162:163], v[160:161], v[162:163], s[30:31] op_sel_hi:[1,1,0]
	v_pk_fma_f32 v[168:169], v[166:167], v[168:169], s[30:31] op_sel_hi:[1,1,0]
	v_pk_add_f32 v[172:173], v[172:173], 1.0 op_sel_hi:[1,0]
	v_pk_fma_f32 v[162:163], v[160:161], v[162:163], s[48:49] op_sel_hi:[1,1,0]
	v_pk_fma_f32 v[168:169], v[166:167], v[168:169], s[48:49] op_sel_hi:[1,1,0]
	v_rcp_f32_e32 v178, v170
	v_pk_fma_f32 v[162:163], v[160:161], v[162:163], s[50:51] op_sel_hi:[1,1,0]
	v_pk_fma_f32 v[168:169], v[166:167], v[168:169], s[50:51] op_sel_hi:[1,1,0]
	v_rcp_f32_e32 v179, v171
	v_pk_fma_f32 v[162:163], v[160:161], v[162:163], s[52:53] op_sel_hi:[1,1,0]
	v_pk_fma_f32 v[168:169], v[166:167], v[168:169], s[52:53] op_sel_hi:[1,1,0]
	v_rcp_f32_e32 v180, v172
	v_pk_fma_f32 v[160:161], v[160:161], v[162:163], s[54:55] op_sel_hi:[1,1,0]
	v_pk_fma_f32 v[166:167], v[166:167], v[168:169], s[54:55] op_sel_hi:[1,1,0]
	v_rcp_f32_e32 v181, v173
	v_pk_fma_f32 v[158:159], v[158:159], v[160:161], 0.5 op_sel_hi:[1,1,0]
	v_pk_fma_f32 v[164:165], v[164:165], v[166:167], 0.5 op_sel_hi:[1,1,0]
	v_pk_mul_f32 v[20:21], v[20:21], v[178:179]
	v_pk_mul_f32 v[24:25], v[24:25], v[158:159]
	v_pk_mul_f32 v[26:27], v[26:27], v[164:165]
	v_pk_mul_f32 v[22:23], v[22:23], v[180:181]
	v_pk_mul_f32 v[28:29], v[28:29], v[32:33]
	v_pk_mul_f32 v[30:31], v[30:31], v[34:35]
	v_pk_mul_f32 v[20:21], v[20:21], v[24:25]
	v_pk_mul_f32 v[22:23], v[22:23], v[26:27]
	v_cvt_pk_bf16_f32 v32, v28, v29
	v_cvt_pk_bf16_f32 v33, v30, v31
	v_cvt_pk_bf16_f32 v34, v20, v21
	v_cvt_pk_bf16_f32 v35, v22, v23
	global_store_dwordx4 v188, v[32:35], s[10:11]
	v_pk_mul_f32 v[16:17], v[16:17], v[250:251] op_sel_hi:[1,0]
	v_pk_mul_f32 v[18:19], v[18:19], v[250:251] op_sel_hi:[1,0]
	v_pk_mul_f32 v[8:9], v[8:9], v[250:251] op_sel_hi:[1,0]
	v_pk_mul_f32 v[10:11], v[10:11], v[250:251] op_sel_hi:[1,0]
	v_pk_mul_f32 v[12:13], v[12:13], v[250:251] op_sel_hi:[1,0]
	v_pk_mul_f32 v[14:15], v[14:15], v[250:251] op_sel_hi:[1,0]
	v_pk_mul_f32 v[4:5], v[4:5], v[250:251] op_sel_hi:[1,0]
	v_pk_mul_f32 v[6:7], v[6:7], v[250:251] op_sel_hi:[1,0]
	v_med3_f32 v158, v16, -4.0, 4.0
	v_med3_f32 v164, v18, -4.0, 4.0
	v_pk_mul_f32 v[170:171], v[12:13], v[190:191] op_sel_hi:[1,0]
	v_med3_f32 v159, v17, -4.0, 4.0
	v_med3_f32 v165, v19, -4.0, 4.0
	v_pk_mul_f32 v[172:173], v[14:15], v[190:191] op_sel_hi:[1,0]
	v_pk_mul_f32 v[160:161], v[158:159], v[158:159]
	v_pk_mul_f32 v[166:167], v[164:165], v[164:165]
	v_exp_f32_e32 v170, v170
	v_pk_fma_f32 v[160:161], v[160:161], s[72:73], -1.0 op_sel_hi:[1,0,0]
	v_pk_fma_f32 v[166:167], v[166:167], s[72:73], -1.0 op_sel_hi:[1,0,0]
	v_exp_f32_e32 v171, v171
	v_pk_fma_f32 v[162:163], v[160:161], s[74:75], v[198:199] op_sel_hi:[1,0,0]
	v_pk_fma_f32 v[168:169], v[166:167], s[74:75], v[198:199] op_sel_hi:[1,0,0]
	v_exp_f32_e32 v172, v172
	v_pk_fma_f32 v[162:163], v[160:161], v[162:163], s[2:3] op_sel_hi:[1,1,0]
	v_pk_fma_f32 v[168:169], v[166:167], v[168:169], s[2:3] op_sel_hi:[1,1,0]
	v_exp_f32_e32 v173, v173
	v_pk_fma_f32 v[162:163], v[160:161], v[162:163], s[28:29] op_sel_hi:[1,1,0]
	v_pk_fma_f32 v[168:169], v[166:167], v[168:169], s[28:29] op_sel_hi:[1,1,0]
	v_pk_add_f32 v[170:171], v[170:171], 1.0 op_sel_hi:[1,0]
	v_pk_fma_f32 v[162:163], v[160:161], v[162:163], s[30:31] op_sel_hi:[1,1,0]
	v_pk_fma_f32 v[168:169], v[166:167], v[168:169], s[30:31] op_sel_hi:[1,1,0]
	v_pk_add_f32 v[172:173], v[172:173], 1.0 op_sel_hi:[1,0]
	v_pk_fma_f32 v[162:163], v[160:161], v[162:163], s[48:49] op_sel_hi:[1,1,0]
	v_pk_fma_f32 v[168:169], v[166:167], v[168:169], s[48:49] op_sel_hi:[1,1,0]
	v_rcp_f32_e32 v178, v170
	v_pk_fma_f32 v[162:163], v[160:161], v[162:163], s[50:51] op_sel_hi:[1,1,0]
	v_pk_fma_f32 v[168:169], v[166:167], v[168:169], s[50:51] op_sel_hi:[1,1,0]
	v_rcp_f32_e32 v179, v171
	v_pk_fma_f32 v[162:163], v[160:161], v[162:163], s[52:53] op_sel_hi:[1,1,0]
	v_pk_fma_f32 v[168:169], v[166:167], v[168:169], s[52:53] op_sel_hi:[1,1,0]
	v_rcp_f32_e32 v180, v172
	v_pk_fma_f32 v[160:161], v[160:161], v[162:163], s[54:55] op_sel_hi:[1,1,0]
	v_pk_fma_f32 v[166:167], v[166:167], v[168:169], s[54:55] op_sel_hi:[1,1,0]
	v_rcp_f32_e32 v181, v173
	v_pk_fma_f32 v[158:159], v[158:159], v[160:161], 0.5 op_sel_hi:[1,1,0]
	v_pk_fma_f32 v[164:165], v[164:165], v[166:167], 0.5 op_sel_hi:[1,1,0]
	v_pk_mul_f32 v[12:13], v[12:13], v[178:179]
	v_pk_mul_f32 v[16:17], v[16:17], v[158:159]
	v_pk_mul_f32 v[18:19], v[18:19], v[164:165]
	v_pk_mul_f32 v[14:15], v[14:15], v[180:181]
	v_med3_f32 v158, v8, -4.0, 4.0
	v_med3_f32 v164, v10, -4.0, 4.0
	v_pk_mul_f32 v[170:171], v[4:5], v[190:191] op_sel_hi:[1,0]
	v_med3_f32 v159, v9, -4.0, 4.0
	v_med3_f32 v165, v11, -4.0, 4.0
	v_pk_mul_f32 v[172:173], v[6:7], v[190:191] op_sel_hi:[1,0]
	v_pk_mul_f32 v[160:161], v[158:159], v[158:159]
	v_pk_mul_f32 v[166:167], v[164:165], v[164:165]
	v_exp_f32_e32 v170, v170
	v_pk_fma_f32 v[160:161], v[160:161], s[72:73], -1.0 op_sel_hi:[1,0,0]
	v_pk_fma_f32 v[166:167], v[166:167], s[72:73], -1.0 op_sel_hi:[1,0,0]
	v_exp_f32_e32 v171, v171
	v_pk_fma_f32 v[162:163], v[160:161], s[74:75], v[198:199] op_sel_hi:[1,0,0]
	v_pk_fma_f32 v[168:169], v[166:167], s[74:75], v[198:199] op_sel_hi:[1,0,0]
	v_exp_f32_e32 v172, v172
	v_pk_fma_f32 v[162:163], v[160:161], v[162:163], s[2:3] op_sel_hi:[1,1,0]
	v_pk_fma_f32 v[168:169], v[166:167], v[168:169], s[2:3] op_sel_hi:[1,1,0]
	v_exp_f32_e32 v173, v173
	v_pk_fma_f32 v[162:163], v[160:161], v[162:163], s[28:29] op_sel_hi:[1,1,0]
	v_pk_fma_f32 v[168:169], v[166:167], v[168:169], s[28:29] op_sel_hi:[1,1,0]
	v_pk_add_f32 v[170:171], v[170:171], 1.0 op_sel_hi:[1,0]
	v_pk_fma_f32 v[162:163], v[160:161], v[162:163], s[30:31] op_sel_hi:[1,1,0]
	v_pk_fma_f32 v[168:169], v[166:167], v[168:169], s[30:31] op_sel_hi:[1,1,0]
	v_pk_add_f32 v[172:173], v[172:173], 1.0 op_sel_hi:[1,0]
	v_pk_fma_f32 v[162:163], v[160:161], v[162:163], s[48:49] op_sel_hi:[1,1,0]
	v_pk_fma_f32 v[168:169], v[166:167], v[168:169], s[48:49] op_sel_hi:[1,1,0]
	v_rcp_f32_e32 v178, v170
	v_pk_fma_f32 v[162:163], v[160:161], v[162:163], s[50:51] op_sel_hi:[1,1,0]
	v_pk_fma_f32 v[168:169], v[166:167], v[168:169], s[50:51] op_sel_hi:[1,1,0]
	v_rcp_f32_e32 v179, v171
	v_pk_fma_f32 v[162:163], v[160:161], v[162:163], s[52:53] op_sel_hi:[1,1,0]
	v_pk_fma_f32 v[168:169], v[166:167], v[168:169], s[52:53] op_sel_hi:[1,1,0]
	v_rcp_f32_e32 v180, v172
	v_pk_fma_f32 v[160:161], v[160:161], v[162:163], s[54:55] op_sel_hi:[1,1,0]
	v_pk_fma_f32 v[166:167], v[166:167], v[168:169], s[54:55] op_sel_hi:[1,1,0]
	v_rcp_f32_e32 v181, v173
	v_pk_fma_f32 v[158:159], v[158:159], v[160:161], 0.5 op_sel_hi:[1,1,0]
	v_pk_fma_f32 v[164:165], v[164:165], v[166:167], 0.5 op_sel_hi:[1,1,0]
	v_pk_mul_f32 v[4:5], v[4:5], v[178:179]
	v_pk_mul_f32 v[8:9], v[8:9], v[158:159]
	v_pk_mul_f32 v[10:11], v[10:11], v[164:165]
	v_pk_mul_f32 v[6:7], v[6:7], v[180:181]
	v_pk_mul_f32 v[12:13], v[12:13], v[16:17]
	v_pk_mul_f32 v[14:15], v[14:15], v[18:19]
	v_pk_mul_f32 v[4:5], v[4:5], v[8:9]
	v_pk_mul_f32 v[6:7], v[6:7], v[10:11]
	v_cvt_pk_bf16_f32 v16, v12, v13
	v_cvt_pk_bf16_f32 v17, v14, v15
	v_cvt_pk_bf16_f32 v18, v4, v5
	v_cvt_pk_bf16_f32 v19, v6, v7
	global_store_dwordx4 v189, v[16:19], s[10:11]
	s_andn2_b64 vcc, exec, s[6:7]
	s_mov_b64 s[0:1], -1
	s_cbranch_vccnz .LBB0_442
